# rownorm hn (bf16 normalized rows) stores made write-through (sc1) so the end-of-phase release fence has little to write back
# baseline (speedup 1.0000x reference)
; __device__ __forceinline__ unsigned cvt_pk_bf16(float lo, float hi) { unsigned r; asm volatile("v_cvt_pk_bf16_f32 %0, %1, %2" : "=v"(r) : "v"(lo), "v"(hi)); return r; }
; __device__ __forceinline__ float bf2f(unsigned short b) { return __uint_as_float(((unsigned)b) << 16); }
; __device__ __forceinline__ void rn_finish(RowRegs& R, bool hasy, const float* gpost, float scale, float* xo, const float* gpre, bf16_t* hn, int lane) {
;     if (hasy) { f32x4 t[4]; float s = 0.f;
; #pragma unroll
;         for (int j = 0; j < 2; ++j) { const u32x4 w = R.y[j];
;             t[2 * j] = (f32x4){bf2f(w.x & 0xffff), bf2f(w.x >> 16), bf2f(w.y & 0xffff), bf2f(w.y >> 16)}; t[2 * j + 1] = (f32x4){bf2f(w.z & 0xffff), bf2f(w.z >> 16), bf2f(w.w & 0xffff), bf2f(w.w >> 16)}; }
; #pragma unroll
;         for (int j = 0; j < 4; ++j) s += (t[j][0] * t[j][0] + t[j][1] * t[j][1]) + (t[j][2] * t[j][2] + t[j][3] * t[j][3]);
;         const float rs = rsqrtf(wave_sum(s) * (1.f / DM) + 1e-6f) * scale;
; #pragma unroll
;         for (int j = 0; j < 4; ++j) { const f32x4 g = *(const f32x4*)(gpost + 512 * (j >> 1) + 8 * lane + 4 * (j & 1)); R.v[j] = R.v[j] + t[j] * g * rs; } }
;     if (xo) {
; #pragma unroll
;         for (int j = 0; j < 4; ++j) __builtin_nontemporal_store(R.v[j], (f32x4*)(xo + 512 * (j >> 1) + 8 * lane + 4 * (j & 1))); }
;     if (hn) { float s = 0.f;
; #pragma unroll
;         for (int j = 0; j < 4; ++j) s += (R.v[j][0] * R.v[j][0] + R.v[j][1] * R.v[j][1]) + (R.v[j][2] * R.v[j][2] + R.v[j][3] * R.v[j][3]);
;         const float rs = rsqrtf(wave_sum(s) * (1.f / DM) + 1e-6f);
; #pragma unroll
;         for (int j = 0; j < 2; ++j) { const f32x4 g0 = *(const f32x4*)(gpre + 512 * j + 8 * lane), g1 = *(const f32x4*)(gpre + 512 * j + 8 * lane + 4); const f32x4 o0 = R.v[2 * j] * g0 * rs, o1 = R.v[2 * j + 1] * g1 * rs;
;             u32x4 w; w.x = cvt_pk_bf16(o0[0], o0[1]); w.y = cvt_pk_bf16(o0[2], o0[3]); w.z = cvt_pk_bf16(o1[0], o1[1]); w.w = cvt_pk_bf16(o1[2], o1[3]); *(u32x4*)(hn + 512 * j + 8 * lane) = w; } }
.Lrn_loop:
	s_mul_i32 s25, s44, 3
	s_add_i32 s25, s25, s24
	s_cmp_lt_i32 s25, 0x10000
	s_cselect_b32 s25, s25, s24
	s_lshl_b32 s34, s25, 12
	s_lshl_b32 s4, s25, 11
	v_lshl_add_u64 v[228:229], v[62:63], 0, s[34:35]
	v_lshl_add_u64 v[230:231], v[52:53], 0, s[4:5]
	global_load_dwordx4 v[162:165], v[228:229], off nt
	global_load_dwordx4 v[166:169], v[228:229], off offset:1024 nt
	global_load_dwordx4 v[170:173], v[228:229], off offset:2048 nt
	global_load_dwordx4 v[174:177], v[228:229], off offset:3072 nt
	global_load_dwordx2 v[178:179], v[230:231], off nt
	global_load_dwordx2 v[180:181], v[230:231], off offset:512 nt
	global_load_dwordx2 v[182:183], v[230:231], off offset:1024 nt
	global_load_dwordx2 v[184:185], v[230:231], off offset:1536 nt
	s_lshl_b32 s18, s24, 12
	s_lshl_b32 s28, s24, 11
	s_andn2_b64 vcc, exec, s[40:41]
	s_waitcnt vmcnt(36)
	v_lshlrev_b32_e32 v206, 16, v18
	v_and_b32_e32 v207, 0xffff0000, v18
	v_lshlrev_b32_e32 v208, 16, v19
	v_and_b32_e32 v209, 0xffff0000, v19
	v_lshlrev_b32_e32 v210, 16, v20
	v_and_b32_e32 v211, 0xffff0000, v20
	v_lshlrev_b32_e32 v212, 16, v21
	v_and_b32_e32 v213, 0xffff0000, v21
	v_lshlrev_b32_e32 v214, 16, v22
	v_and_b32_e32 v215, 0xffff0000, v22
	v_lshlrev_b32_e32 v216, 16, v23
	v_and_b32_e32 v217, 0xffff0000, v23
	v_lshlrev_b32_e32 v218, 16, v24
	v_and_b32_e32 v219, 0xffff0000, v24
	v_lshlrev_b32_e32 v220, 16, v25
	v_and_b32_e32 v221, 0xffff0000, v25
	v_pk_mul_f32 v[222:223], v[206:207], v[206:207]
	v_pk_fma_f32 v[222:223], v[208:209], v[208:209], v[222:223]
	v_pk_fma_f32 v[222:223], v[210:211], v[210:211], v[222:223]
	v_pk_fma_f32 v[222:223], v[212:213], v[212:213], v[222:223]
	v_pk_fma_f32 v[222:223], v[214:215], v[214:215], v[222:223]
	v_pk_fma_f32 v[222:223], v[216:217], v[216:217], v[222:223]
	v_pk_fma_f32 v[222:223], v[218:219], v[218:219], v[222:223]
	v_pk_fma_f32 v[222:223], v[220:221], v[220:221], v[222:223]
	v_lshl_add_u64 v[228:229], v[56:57], 0, s[18:19]
	v_add_f32_e32 v224, v222, v223
	s_nop 1
	v_add_f32_dpp v224, v224, v224 quad_perm:[1,0,3,2] row_mask:0xf bank_mask:0xf bound_ctrl:1
	s_nop 1
	v_add_f32_dpp v224, v224, v224 quad_perm:[2,3,0,1] row_mask:0xf bank_mask:0xf bound_ctrl:1
	s_nop 1
	v_add_f32_dpp v224, v224, v224 row_half_mirror row_mask:0xf bank_mask:0xf bound_ctrl:1
	s_nop 1
	v_add_f32_dpp v224, v224, v224 row_mirror row_mask:0xf bank_mask:0xf bound_ctrl:1
	v_mov_b32_e32 v225, v224
	s_nop 1
	v_permlane16_swap_b32_e32 v224, v225
	v_add_f32_e32 v224, v224, v225
	v_mov_b32_e32 v225, v224
	s_nop 1
	v_permlane32_swap_b32_e32 v224, v225
	v_add_f32_e32 v224, v224, v225
	v_fmamk_f32 v224, v224, 0x3a800000, v197
	v_rsq_f32_e32 v224, v224
	v_lshl_add_u64 v[230:231], v[60:61], 0, s[28:29]
	v_mul_f32_e32 v226, v69, v224
	v_pk_mul_f32 v[206:207], v[206:207], v[96:97]
	v_pk_mul_f32 v[208:209], v[208:209], v[98:99]
	v_pk_mul_f32 v[210:211], v[210:211], v[100:101]
	v_pk_mul_f32 v[212:213], v[212:213], v[102:103]
	v_pk_mul_f32 v[214:215], v[214:215], v[104:105]
	v_pk_mul_f32 v[216:217], v[216:217], v[106:107]
	v_pk_mul_f32 v[218:219], v[218:219], v[108:109]
	v_pk_mul_f32 v[220:221], v[220:221], v[110:111]
	v_pk_fma_f32 v[2:3], v[206:207], v[226:227], v[2:3] op_sel_hi:[1,0,1]
	v_pk_fma_f32 v[4:5], v[208:209], v[226:227], v[4:5] op_sel_hi:[1,0,1]
	v_pk_fma_f32 v[6:7], v[210:211], v[226:227], v[6:7] op_sel_hi:[1,0,1]
	v_pk_fma_f32 v[8:9], v[212:213], v[226:227], v[8:9] op_sel_hi:[1,0,1]
	v_pk_fma_f32 v[10:11], v[214:215], v[226:227], v[10:11] op_sel_hi:[1,0,1]
	v_pk_fma_f32 v[12:13], v[216:217], v[226:227], v[12:13] op_sel_hi:[1,0,1]
	v_pk_fma_f32 v[14:15], v[218:219], v[226:227], v[14:15] op_sel_hi:[1,0,1]
	v_pk_fma_f32 v[16:17], v[220:221], v[226:227], v[16:17] op_sel_hi:[1,0,1]
	global_store_dwordx4 v[228:229], v[2:5], off nt
	global_store_dwordx4 v[228:229], v[6:9], off offset:1024 nt
	global_store_dwordx4 v[228:229], v[10:13], off offset:2048 nt
	global_store_dwordx4 v[228:229], v[14:17], off offset:3072 nt
	s_cbranch_vccnz .Lrn_skip0
	v_pk_mul_f32 v[222:223], v[2:3], v[2:3]
	v_pk_fma_f32 v[222:223], v[4:5], v[4:5], v[222:223]
	v_pk_fma_f32 v[222:223], v[6:7], v[6:7], v[222:223]
	v_pk_fma_f32 v[222:223], v[8:9], v[8:9], v[222:223]
	v_pk_fma_f32 v[222:223], v[10:11], v[10:11], v[222:223]
	v_pk_fma_f32 v[222:223], v[12:13], v[12:13], v[222:223]
	v_pk_fma_f32 v[222:223], v[14:15], v[14:15], v[222:223]
	v_pk_fma_f32 v[222:223], v[16:17], v[16:17], v[222:223]
	v_pk_mul_f32 v[232:233], v[2:3], v[112:113]
	v_pk_mul_f32 v[234:235], v[4:5], v[114:115]
	v_pk_mul_f32 v[236:237], v[6:7], v[116:117]
	v_pk_mul_f32 v[238:239], v[8:9], v[118:119]
	v_pk_mul_f32 v[240:241], v[10:11], v[120:121]
	v_pk_mul_f32 v[242:243], v[12:13], v[122:123]
	v_pk_mul_f32 v[244:245], v[14:15], v[124:125]
	v_pk_mul_f32 v[246:247], v[16:17], v[126:127]
	v_add_f32_e32 v224, v222, v223
	s_nop 1
	v_add_f32_dpp v224, v224, v224 quad_perm:[1,0,3,2] row_mask:0xf bank_mask:0xf bound_ctrl:1
	s_nop 1
	v_add_f32_dpp v224, v224, v224 quad_perm:[2,3,0,1] row_mask:0xf bank_mask:0xf bound_ctrl:1
	s_nop 1
	v_add_f32_dpp v224, v224, v224 row_half_mirror row_mask:0xf bank_mask:0xf bound_ctrl:1
	s_nop 1
	v_add_f32_dpp v224, v224, v224 row_mirror row_mask:0xf bank_mask:0xf bound_ctrl:1
	v_mov_b32_e32 v225, v224
	s_nop 1
	v_permlane16_swap_b32_e32 v224, v225
	v_add_f32_e32 v224, v224, v225
	v_mov_b32_e32 v225, v224
	s_nop 1
	v_permlane32_swap_b32_e32 v224, v225
	v_add_f32_e32 v224, v224, v225
	v_fmamk_f32 v224, v224, 0x3a800000, v197
	v_rsq_f32_e32 v226, v224
	s_nop 0
	v_pk_mul_f32 v[232:233], v[232:233], v[226:227] op_sel_hi:[1,0]
	v_pk_mul_f32 v[234:235], v[234:235], v[226:227] op_sel_hi:[1,0]
	v_pk_mul_f32 v[236:237], v[236:237], v[226:227] op_sel_hi:[1,0]
	v_pk_mul_f32 v[238:239], v[238:239], v[226:227] op_sel_hi:[1,0]
	v_pk_mul_f32 v[240:241], v[240:241], v[226:227] op_sel_hi:[1,0]
	v_pk_mul_f32 v[242:243], v[242:243], v[226:227] op_sel_hi:[1,0]
	v_pk_mul_f32 v[244:245], v[244:245], v[226:227] op_sel_hi:[1,0]
	v_pk_mul_f32 v[246:247], v[246:247], v[226:227] op_sel_hi:[1,0]
	v_cvt_pk_bf16_f32 v248, v232, v233
	v_cvt_pk_bf16_f32 v249, v234, v235
	global_store_dwordx2 v[230:231], v[248:249], off offset:0 sc1
	v_cvt_pk_bf16_f32 v250, v236, v237
	v_cvt_pk_bf16_f32 v251, v238, v239
	global_store_dwordx2 v[230:231], v[250:251], off offset:512 sc1
	v_cvt_pk_bf16_f32 v248, v240, v241
	v_cvt_pk_bf16_f32 v249, v242, v243
	global_store_dwordx2 v[230:231], v[248:249], off offset:1024 sc1
	v_cvt_pk_bf16_f32 v250, v244, v245
	v_cvt_pk_bf16_f32 v251, v246, v247
	global_store_dwordx2 v[230:231], v[250:251], off offset:1536 sc1
; __device__ __forceinline__ unsigned cvt_pk_bf16(float lo, float hi) { unsigned r; asm volatile("v_cvt_pk_bf16_f32 %0, %1, %2" : "=v"(r) : "v"(lo), "v"(hi)); return r; }
; __device__ __forceinline__ float bf2f(unsigned short b) { return __uint_as_float(((unsigned)b) << 16); }
; __device__ __forceinline__ void rn_finish(RowRegs& R, bool hasy, const float* gpost, float scale, float* xo, const float* gpre, bf16_t* hn, int lane) {
;     if (hasy) { f32x4 t[4]; float s = 0.f;
; #pragma unroll
;         for (int j = 0; j < 2; ++j) { const u32x4 w = R.y[j];
;             t[2 * j] = (f32x4){bf2f(w.x & 0xffff), bf2f(w.x >> 16), bf2f(w.y & 0xffff), bf2f(w.y >> 16)}; t[2 * j + 1] = (f32x4){bf2f(w.z & 0xffff), bf2f(w.z >> 16), bf2f(w.w & 0xffff), bf2f(w.w >> 16)}; }
; #pragma unroll
;         for (int j = 0; j < 4; ++j) s += (t[j][0] * t[j][0] + t[j][1] * t[j][1]) + (t[j][2] * t[j][2] + t[j][3] * t[j][3]);
;         const float rs = rsqrtf(wave_sum(s) * (1.f / DM) + 1e-6f) * scale;
; #pragma unroll
;         for (int j = 0; j < 4; ++j) { const f32x4 g = *(const f32x4*)(gpost + 512 * (j >> 1) + 8 * lane + 4 * (j & 1)); R.v[j] = R.v[j] + t[j] * g * rs; } }
;     if (xo) {
; #pragma unroll
;         for (int j = 0; j < 4; ++j) __builtin_nontemporal_store(R.v[j], (f32x4*)(xo + 512 * (j >> 1) + 8 * lane + 4 * (j & 1))); }
;     if (hn) { float s = 0.f;
; #pragma unroll
;         for (int j = 0; j < 4; ++j) s += (R.v[j][0] * R.v[j][0] + R.v[j][1] * R.v[j][1]) + (R.v[j][2] * R.v[j][2] + R.v[j][3] * R.v[j][3]);
;         const float rs = rsqrtf(wave_sum(s) * (1.f / DM) + 1e-6f);
; #pragma unroll
;         for (int j = 0; j < 2; ++j) { const f32x4 g0 = *(const f32x4*)(gpre + 512 * j + 8 * lane), g1 = *(const f32x4*)(gpre + 512 * j + 8 * lane + 4); const f32x4 o0 = R.v[2 * j] * g0 * rs, o1 = R.v[2 * j + 1] * g1 * rs;
;             u32x4 w; w.x = cvt_pk_bf16(o0[0], o0[1]); w.y = cvt_pk_bf16(o0[2], o0[3]); w.z = cvt_pk_bf16(o1[0], o1[1]); w.w = cvt_pk_bf16(o1[2], o1[3]); *(u32x4*)(hn + 512 * j + 8 * lane) = w; } }
.Lrn_skip0:
	s_add_i32 s24, s24, s44
	s_cmp_gt_i32 s24, 0xffff
	s_cbranch_scc1 .Lrn_exit
	s_mul_i32 s25, s44, 3
	s_add_i32 s25, s25, s24
	s_cmp_lt_i32 s25, 0x10000
	s_cselect_b32 s25, s25, s24
	s_lshl_b32 s34, s25, 12
	s_lshl_b32 s4, s25, 11
	v_lshl_add_u64 v[228:229], v[62:63], 0, s[34:35]
	v_lshl_add_u64 v[230:231], v[52:53], 0, s[4:5]
	global_load_dwordx4 v[2:5], v[228:229], off nt
	global_load_dwordx4 v[6:9], v[228:229], off offset:1024 nt
	global_load_dwordx4 v[10:13], v[228:229], off offset:2048 nt
	global_load_dwordx4 v[14:17], v[228:229], off offset:3072 nt
	global_load_dwordx2 v[18:19], v[230:231], off nt
	global_load_dwordx2 v[20:21], v[230:231], off offset:512 nt
	global_load_dwordx2 v[22:23], v[230:231], off offset:1024 nt
	global_load_dwordx2 v[24:25], v[230:231], off offset:1536 nt
	s_lshl_b32 s18, s24, 12
	s_lshl_b32 s28, s24, 11
	s_andn2_b64 vcc, exec, s[40:41]
	s_waitcnt vmcnt(36)
	v_lshlrev_b32_e32 v206, 16, v42
	v_and_b32_e32 v207, 0xffff0000, v42
	v_lshlrev_b32_e32 v208, 16, v43
	v_and_b32_e32 v209, 0xffff0000, v43
	v_lshlrev_b32_e32 v210, 16, v44
	v_and_b32_e32 v211, 0xffff0000, v44
	v_lshlrev_b32_e32 v212, 16, v45
	v_and_b32_e32 v213, 0xffff0000, v45
	v_lshlrev_b32_e32 v214, 16, v46
	v_and_b32_e32 v215, 0xffff0000, v46
	v_lshlrev_b32_e32 v216, 16, v47
	v_and_b32_e32 v217, 0xffff0000, v47
	v_lshlrev_b32_e32 v218, 16, v48
	v_and_b32_e32 v219, 0xffff0000, v48
	v_lshlrev_b32_e32 v220, 16, v49
	v_and_b32_e32 v221, 0xffff0000, v49
	v_pk_mul_f32 v[222:223], v[206:207], v[206:207]
	v_pk_fma_f32 v[222:223], v[208:209], v[208:209], v[222:223]
	v_pk_fma_f32 v[222:223], v[210:211], v[210:211], v[222:223]
	v_pk_fma_f32 v[222:223], v[212:213], v[212:213], v[222:223]
	v_pk_fma_f32 v[222:223], v[214:215], v[214:215], v[222:223]
	v_pk_fma_f32 v[222:223], v[216:217], v[216:217], v[222:223]
	v_pk_fma_f32 v[222:223], v[218:219], v[218:219], v[222:223]
	v_pk_fma_f32 v[222:223], v[220:221], v[220:221], v[222:223]
	v_lshl_add_u64 v[228:229], v[56:57], 0, s[18:19]
	v_add_f32_e32 v224, v222, v223
	s_nop 1
	v_add_f32_dpp v224, v224, v224 quad_perm:[1,0,3,2] row_mask:0xf bank_mask:0xf bound_ctrl:1
	s_nop 1
	v_add_f32_dpp v224, v224, v224 quad_perm:[2,3,0,1] row_mask:0xf bank_mask:0xf bound_ctrl:1
	s_nop 1
	v_add_f32_dpp v224, v224, v224 row_half_mirror row_mask:0xf bank_mask:0xf bound_ctrl:1
	s_nop 1
	v_add_f32_dpp v224, v224, v224 row_mirror row_mask:0xf bank_mask:0xf bound_ctrl:1
	v_mov_b32_e32 v225, v224
	s_nop 1
	v_permlane16_swap_b32_e32 v224, v225
	v_add_f32_e32 v224, v224, v225
	v_mov_b32_e32 v225, v224
	s_nop 1
	v_permlane32_swap_b32_e32 v224, v225
	v_add_f32_e32 v224, v224, v225
	v_fmamk_f32 v224, v224, 0x3a800000, v197
	v_rsq_f32_e32 v224, v224
	v_lshl_add_u64 v[230:231], v[60:61], 0, s[28:29]
	v_mul_f32_e32 v226, v69, v224
	v_pk_mul_f32 v[206:207], v[206:207], v[96:97]
	v_pk_mul_f32 v[208:209], v[208:209], v[98:99]
	v_pk_mul_f32 v[210:211], v[210:211], v[100:101]
	v_pk_mul_f32 v[212:213], v[212:213], v[102:103]
	v_pk_mul_f32 v[214:215], v[214:215], v[104:105]
	v_pk_mul_f32 v[216:217], v[216:217], v[106:107]
	v_pk_mul_f32 v[218:219], v[218:219], v[108:109]
	v_pk_mul_f32 v[220:221], v[220:221], v[110:111]
	v_pk_fma_f32 v[26:27], v[206:207], v[226:227], v[26:27] op_sel_hi:[1,0,1]
	v_pk_fma_f32 v[28:29], v[208:209], v[226:227], v[28:29] op_sel_hi:[1,0,1]
	v_pk_fma_f32 v[30:31], v[210:211], v[226:227], v[30:31] op_sel_hi:[1,0,1]
	v_pk_fma_f32 v[32:33], v[212:213], v[226:227], v[32:33] op_sel_hi:[1,0,1]
	v_pk_fma_f32 v[34:35], v[214:215], v[226:227], v[34:35] op_sel_hi:[1,0,1]
	v_pk_fma_f32 v[36:37], v[216:217], v[226:227], v[36:37] op_sel_hi:[1,0,1]
	v_pk_fma_f32 v[38:39], v[218:219], v[226:227], v[38:39] op_sel_hi:[1,0,1]
	v_pk_fma_f32 v[40:41], v[220:221], v[226:227], v[40:41] op_sel_hi:[1,0,1]
	global_store_dwordx4 v[228:229], v[26:29], off nt
	global_store_dwordx4 v[228:229], v[30:33], off offset:1024 nt
	global_store_dwordx4 v[228:229], v[34:37], off offset:2048 nt
	global_store_dwordx4 v[228:229], v[38:41], off offset:3072 nt
	s_cbranch_vccnz .Lrn_skip1
	v_pk_mul_f32 v[222:223], v[26:27], v[26:27]
	v_pk_fma_f32 v[222:223], v[28:29], v[28:29], v[222:223]
	v_pk_fma_f32 v[222:223], v[30:31], v[30:31], v[222:223]
	v_pk_fma_f32 v[222:223], v[32:33], v[32:33], v[222:223]
	v_pk_fma_f32 v[222:223], v[34:35], v[34:35], v[222:223]
	v_pk_fma_f32 v[222:223], v[36:37], v[36:37], v[222:223]
	v_pk_fma_f32 v[222:223], v[38:39], v[38:39], v[222:223]
	v_pk_fma_f32 v[222:223], v[40:41], v[40:41], v[222:223]
	v_pk_mul_f32 v[232:233], v[26:27], v[112:113]
	v_pk_mul_f32 v[234:235], v[28:29], v[114:115]
	v_pk_mul_f32 v[236:237], v[30:31], v[116:117]
	v_pk_mul_f32 v[238:239], v[32:33], v[118:119]
	v_pk_mul_f32 v[240:241], v[34:35], v[120:121]
	v_pk_mul_f32 v[242:243], v[36:37], v[122:123]
	v_pk_mul_f32 v[244:245], v[38:39], v[124:125]
	v_pk_mul_f32 v[246:247], v[40:41], v[126:127]
	v_add_f32_e32 v224, v222, v223
	s_nop 1
	v_add_f32_dpp v224, v224, v224 quad_perm:[1,0,3,2] row_mask:0xf bank_mask:0xf bound_ctrl:1
	s_nop 1
	v_add_f32_dpp v224, v224, v224 quad_perm:[2,3,0,1] row_mask:0xf bank_mask:0xf bound_ctrl:1
	s_nop 1
	v_add_f32_dpp v224, v224, v224 row_half_mirror row_mask:0xf bank_mask:0xf bound_ctrl:1
	s_nop 1
	v_add_f32_dpp v224, v224, v224 row_mirror row_mask:0xf bank_mask:0xf bound_ctrl:1
	v_mov_b32_e32 v225, v224
	s_nop 1
	v_permlane16_swap_b32_e32 v224, v225
	v_add_f32_e32 v224, v224, v225
	v_mov_b32_e32 v225, v224
	s_nop 1
	v_permlane32_swap_b32_e32 v224, v225
	v_add_f32_e32 v224, v224, v225
	v_fmamk_f32 v224, v224, 0x3a800000, v197
	v_rsq_f32_e32 v226, v224
	s_nop 0
	v_pk_mul_f32 v[232:233], v[232:233], v[226:227] op_sel_hi:[1,0]
	v_pk_mul_f32 v[234:235], v[234:235], v[226:227] op_sel_hi:[1,0]
	v_pk_mul_f32 v[236:237], v[236:237], v[226:227] op_sel_hi:[1,0]
	v_pk_mul_f32 v[238:239], v[238:239], v[226:227] op_sel_hi:[1,0]
	v_pk_mul_f32 v[240:241], v[240:241], v[226:227] op_sel_hi:[1,0]
	v_pk_mul_f32 v[242:243], v[242:243], v[226:227] op_sel_hi:[1,0]
	v_pk_mul_f32 v[244:245], v[244:245], v[226:227] op_sel_hi:[1,0]
	v_pk_mul_f32 v[246:247], v[246:247], v[226:227] op_sel_hi:[1,0]
	v_cvt_pk_bf16_f32 v248, v232, v233
	v_cvt_pk_bf16_f32 v249, v234, v235
	global_store_dwordx2 v[230:231], v[248:249], off offset:0 sc1
	v_cvt_pk_bf16_f32 v250, v236, v237
	v_cvt_pk_bf16_f32 v251, v238, v239
	global_store_dwordx2 v[230:231], v[250:251], off offset:512 sc1
	v_cvt_pk_bf16_f32 v248, v240, v241
	v_cvt_pk_bf16_f32 v249, v242, v243
	global_store_dwordx2 v[230:231], v[248:249], off offset:1024 sc1
	v_cvt_pk_bf16_f32 v250, v244, v245
	v_cvt_pk_bf16_f32 v251, v246, v247
	global_store_dwordx2 v[230:231], v[250:251], off offset:1536 sc1
; __device__ __forceinline__ unsigned cvt_pk_bf16(float lo, float hi) { unsigned r; asm volatile("v_cvt_pk_bf16_f32 %0, %1, %2" : "=v"(r) : "v"(lo), "v"(hi)); return r; }
; __device__ __forceinline__ float bf2f(unsigned short b) { return __uint_as_float(((unsigned)b) << 16); }
; __device__ __forceinline__ void rn_finish(RowRegs& R, bool hasy, const float* gpost, float scale, float* xo, const float* gpre, bf16_t* hn, int lane) {
;     if (hasy) { f32x4 t[4]; float s = 0.f;
; #pragma unroll
;         for (int j = 0; j < 2; ++j) { const u32x4 w = R.y[j];
;             t[2 * j] = (f32x4){bf2f(w.x & 0xffff), bf2f(w.x >> 16), bf2f(w.y & 0xffff), bf2f(w.y >> 16)}; t[2 * j + 1] = (f32x4){bf2f(w.z & 0xffff), bf2f(w.z >> 16), bf2f(w.w & 0xffff), bf2f(w.w >> 16)}; }
; #pragma unroll
;         for (int j = 0; j < 4; ++j) s += (t[j][0] * t[j][0] + t[j][1] * t[j][1]) + (t[j][2] * t[j][2] + t[j][3] * t[j][3]);
;         const float rs = rsqrtf(wave_sum(s) * (1.f / DM) + 1e-6f) * scale;
; #pragma unroll
;         for (int j = 0; j < 4; ++j) { const f32x4 g = *(const f32x4*)(gpost + 512 * (j >> 1) + 8 * lane + 4 * (j & 1)); R.v[j] = R.v[j] + t[j] * g * rs; } }
;     if (xo) {
; #pragma unroll
;         for (int j = 0; j < 4; ++j) __builtin_nontemporal_store(R.v[j], (f32x4*)(xo + 512 * (j >> 1) + 8 * lane + 4 * (j & 1))); }
;     if (hn) { float s = 0.f;
; #pragma unroll
;         for (int j = 0; j < 4; ++j) s += (R.v[j][0] * R.v[j][0] + R.v[j][1] * R.v[j][1]) + (R.v[j][2] * R.v[j][2] + R.v[j][3] * R.v[j][3]);
;         const float rs = rsqrtf(wave_sum(s) * (1.f / DM) + 1e-6f);
; #pragma unroll
;         for (int j = 0; j < 2; ++j) { const f32x4 g0 = *(const f32x4*)(gpre + 512 * j + 8 * lane), g1 = *(const f32x4*)(gpre + 512 * j + 8 * lane + 4); const f32x4 o0 = R.v[2 * j] * g0 * rs, o1 = R.v[2 * j + 1] * g1 * rs;
;             u32x4 w; w.x = cvt_pk_bf16(o0[0], o0[1]); w.y = cvt_pk_bf16(o0[2], o0[3]); w.z = cvt_pk_bf16(o1[0], o1[1]); w.w = cvt_pk_bf16(o1[2], o1[3]); *(u32x4*)(hn + 512 * j + 8 * lane) = w; } }
.Lrn_skip1:
	s_add_i32 s24, s24, s44
	s_cmp_gt_i32 s24, 0xffff
	s_cbranch_scc1 .Lrn_exit
	s_mul_i32 s25, s44, 3
	s_add_i32 s25, s25, s24
	s_cmp_lt_i32 s25, 0x10000
	s_cselect_b32 s25, s25, s24
	s_lshl_b32 s34, s25, 12
	s_lshl_b32 s4, s25, 11
	v_lshl_add_u64 v[228:229], v[62:63], 0, s[34:35]
	v_lshl_add_u64 v[230:231], v[52:53], 0, s[4:5]
	global_load_dwordx4 v[26:29], v[228:229], off nt
	global_load_dwordx4 v[30:33], v[228:229], off offset:1024 nt
	global_load_dwordx4 v[34:37], v[228:229], off offset:2048 nt
	global_load_dwordx4 v[38:41], v[228:229], off offset:3072 nt
	global_load_dwordx2 v[42:43], v[230:231], off nt
	global_load_dwordx2 v[44:45], v[230:231], off offset:512 nt
	global_load_dwordx2 v[46:47], v[230:231], off offset:1024 nt
	global_load_dwordx2 v[48:49], v[230:231], off offset:1536 nt
	s_lshl_b32 s18, s24, 12
	s_lshl_b32 s28, s24, 11
	s_andn2_b64 vcc, exec, s[40:41]
	s_waitcnt vmcnt(36)
	v_lshlrev_b32_e32 v206, 16, v86
	v_and_b32_e32 v207, 0xffff0000, v86
	v_lshlrev_b32_e32 v208, 16, v87
	v_and_b32_e32 v209, 0xffff0000, v87
	v_lshlrev_b32_e32 v210, 16, v88
	v_and_b32_e32 v211, 0xffff0000, v88
	v_lshlrev_b32_e32 v212, 16, v89
	v_and_b32_e32 v213, 0xffff0000, v89
	v_lshlrev_b32_e32 v214, 16, v90
	v_and_b32_e32 v215, 0xffff0000, v90
	v_lshlrev_b32_e32 v216, 16, v91
	v_and_b32_e32 v217, 0xffff0000, v91
	v_lshlrev_b32_e32 v218, 16, v92
	v_and_b32_e32 v219, 0xffff0000, v92
	v_lshlrev_b32_e32 v220, 16, v93
	v_and_b32_e32 v221, 0xffff0000, v93
	v_pk_mul_f32 v[222:223], v[206:207], v[206:207]
	v_pk_fma_f32 v[222:223], v[208:209], v[208:209], v[222:223]
	v_pk_fma_f32 v[222:223], v[210:211], v[210:211], v[222:223]
	v_pk_fma_f32 v[222:223], v[212:213], v[212:213], v[222:223]
	v_pk_fma_f32 v[222:223], v[214:215], v[214:215], v[222:223]
	v_pk_fma_f32 v[222:223], v[216:217], v[216:217], v[222:223]
	v_pk_fma_f32 v[222:223], v[218:219], v[218:219], v[222:223]
	v_pk_fma_f32 v[222:223], v[220:221], v[220:221], v[222:223]
	v_lshl_add_u64 v[228:229], v[56:57], 0, s[18:19]
	v_add_f32_e32 v224, v222, v223
	s_nop 1
	v_add_f32_dpp v224, v224, v224 quad_perm:[1,0,3,2] row_mask:0xf bank_mask:0xf bound_ctrl:1
	s_nop 1
	v_add_f32_dpp v224, v224, v224 quad_perm:[2,3,0,1] row_mask:0xf bank_mask:0xf bound_ctrl:1
	s_nop 1
	v_add_f32_dpp v224, v224, v224 row_half_mirror row_mask:0xf bank_mask:0xf bound_ctrl:1
	s_nop 1
	v_add_f32_dpp v224, v224, v224 row_mirror row_mask:0xf bank_mask:0xf bound_ctrl:1
	v_mov_b32_e32 v225, v224
	s_nop 1
	v_permlane16_swap_b32_e32 v224, v225
	v_add_f32_e32 v224, v224, v225
	v_mov_b32_e32 v225, v224
	s_nop 1
	v_permlane32_swap_b32_e32 v224, v225
	v_add_f32_e32 v224, v224, v225
	v_fmamk_f32 v224, v224, 0x3a800000, v197
	v_rsq_f32_e32 v224, v224
	v_lshl_add_u64 v[230:231], v[60:61], 0, s[28:29]
	v_mul_f32_e32 v226, v69, v224
	v_pk_mul_f32 v[206:207], v[206:207], v[96:97]
	v_pk_mul_f32 v[208:209], v[208:209], v[98:99]
	v_pk_mul_f32 v[210:211], v[210:211], v[100:101]
	v_pk_mul_f32 v[212:213], v[212:213], v[102:103]
	v_pk_mul_f32 v[214:215], v[214:215], v[104:105]
	v_pk_mul_f32 v[216:217], v[216:217], v[106:107]
	v_pk_mul_f32 v[218:219], v[218:219], v[108:109]
	v_pk_mul_f32 v[220:221], v[220:221], v[110:111]
	v_pk_fma_f32 v[70:71], v[206:207], v[226:227], v[70:71] op_sel_hi:[1,0,1]
	v_pk_fma_f32 v[72:73], v[208:209], v[226:227], v[72:73] op_sel_hi:[1,0,1]
	v_pk_fma_f32 v[74:75], v[210:211], v[226:227], v[74:75] op_sel_hi:[1,0,1]
	v_pk_fma_f32 v[76:77], v[212:213], v[226:227], v[76:77] op_sel_hi:[1,0,1]
	v_pk_fma_f32 v[78:79], v[214:215], v[226:227], v[78:79] op_sel_hi:[1,0,1]
	v_pk_fma_f32 v[80:81], v[216:217], v[226:227], v[80:81] op_sel_hi:[1,0,1]
	v_pk_fma_f32 v[82:83], v[218:219], v[226:227], v[82:83] op_sel_hi:[1,0,1]
	v_pk_fma_f32 v[84:85], v[220:221], v[226:227], v[84:85] op_sel_hi:[1,0,1]
	global_store_dwordx4 v[228:229], v[70:73], off nt
	global_store_dwordx4 v[228:229], v[74:77], off offset:1024 nt
	global_store_dwordx4 v[228:229], v[78:81], off offset:2048 nt
	global_store_dwordx4 v[228:229], v[82:85], off offset:3072 nt
	s_cbranch_vccnz .Lrn_skip2
	v_pk_mul_f32 v[222:223], v[70:71], v[70:71]
	v_pk_fma_f32 v[222:223], v[72:73], v[72:73], v[222:223]
	v_pk_fma_f32 v[222:223], v[74:75], v[74:75], v[222:223]
	v_pk_fma_f32 v[222:223], v[76:77], v[76:77], v[222:223]
	v_pk_fma_f32 v[222:223], v[78:79], v[78:79], v[222:223]
	v_pk_fma_f32 v[222:223], v[80:81], v[80:81], v[222:223]
	v_pk_fma_f32 v[222:223], v[82:83], v[82:83], v[222:223]
	v_pk_fma_f32 v[222:223], v[84:85], v[84:85], v[222:223]
	v_pk_mul_f32 v[232:233], v[70:71], v[112:113]
	v_pk_mul_f32 v[234:235], v[72:73], v[114:115]
	v_pk_mul_f32 v[236:237], v[74:75], v[116:117]
	v_pk_mul_f32 v[238:239], v[76:77], v[118:119]
	v_pk_mul_f32 v[240:241], v[78:79], v[120:121]
	v_pk_mul_f32 v[242:243], v[80:81], v[122:123]
	v_pk_mul_f32 v[244:245], v[82:83], v[124:125]
	v_pk_mul_f32 v[246:247], v[84:85], v[126:127]
	v_add_f32_e32 v224, v222, v223
	s_nop 1
	v_add_f32_dpp v224, v224, v224 quad_perm:[1,0,3,2] row_mask:0xf bank_mask:0xf bound_ctrl:1
	s_nop 1
	v_add_f32_dpp v224, v224, v224 quad_perm:[2,3,0,1] row_mask:0xf bank_mask:0xf bound_ctrl:1
	s_nop 1
	v_add_f32_dpp v224, v224, v224 row_half_mirror row_mask:0xf bank_mask:0xf bound_ctrl:1
	s_nop 1
	v_add_f32_dpp v224, v224, v224 row_mirror row_mask:0xf bank_mask:0xf bound_ctrl:1
	v_mov_b32_e32 v225, v224
	s_nop 1
	v_permlane16_swap_b32_e32 v224, v225
	v_add_f32_e32 v224, v224, v225
	v_mov_b32_e32 v225, v224
	s_nop 1
	v_permlane32_swap_b32_e32 v224, v225
	v_add_f32_e32 v224, v224, v225
	v_fmamk_f32 v224, v224, 0x3a800000, v197
	v_rsq_f32_e32 v226, v224
	s_nop 0
	v_pk_mul_f32 v[232:233], v[232:233], v[226:227] op_sel_hi:[1,0]
	v_pk_mul_f32 v[234:235], v[234:235], v[226:227] op_sel_hi:[1,0]
	v_pk_mul_f32 v[236:237], v[236:237], v[226:227] op_sel_hi:[1,0]
	v_pk_mul_f32 v[238:239], v[238:239], v[226:227] op_sel_hi:[1,0]
	v_pk_mul_f32 v[240:241], v[240:241], v[226:227] op_sel_hi:[1,0]
	v_pk_mul_f32 v[242:243], v[242:243], v[226:227] op_sel_hi:[1,0]
	v_pk_mul_f32 v[244:245], v[244:245], v[226:227] op_sel_hi:[1,0]
	v_pk_mul_f32 v[246:247], v[246:247], v[226:227] op_sel_hi:[1,0]
	v_cvt_pk_bf16_f32 v248, v232, v233
	v_cvt_pk_bf16_f32 v249, v234, v235
	global_store_dwordx2 v[230:231], v[248:249], off offset:0 sc1
	v_cvt_pk_bf16_f32 v250, v236, v237
	v_cvt_pk_bf16_f32 v251, v238, v239
	global_store_dwordx2 v[230:231], v[250:251], off offset:512 sc1
	v_cvt_pk_bf16_f32 v248, v240, v241
	v_cvt_pk_bf16_f32 v249, v242, v243
	global_store_dwordx2 v[230:231], v[248:249], off offset:1024 sc1
	v_cvt_pk_bf16_f32 v250, v244, v245
	v_cvt_pk_bf16_f32 v251, v246, v247
	global_store_dwordx2 v[230:231], v[250:251], off offset:1536 sc1
; __device__ __forceinline__ unsigned cvt_pk_bf16(float lo, float hi) { unsigned r; asm volatile("v_cvt_pk_bf16_f32 %0, %1, %2" : "=v"(r) : "v"(lo), "v"(hi)); return r; }
; __device__ __forceinline__ float bf2f(unsigned short b) { return __uint_as_float(((unsigned)b) << 16); }
; __device__ __forceinline__ void rn_finish(RowRegs& R, bool hasy, const float* gpost, float scale, float* xo, const float* gpre, bf16_t* hn, int lane) {
;     if (hasy) { f32x4 t[4]; float s = 0.f;
; #pragma unroll
;         for (int j = 0; j < 2; ++j) { const u32x4 w = R.y[j];
;             t[2 * j] = (f32x4){bf2f(w.x & 0xffff), bf2f(w.x >> 16), bf2f(w.y & 0xffff), bf2f(w.y >> 16)}; t[2 * j + 1] = (f32x4){bf2f(w.z & 0xffff), bf2f(w.z >> 16), bf2f(w.w & 0xffff), bf2f(w.w >> 16)}; }
; #pragma unroll
;         for (int j = 0; j < 4; ++j) s += (t[j][0] * t[j][0] + t[j][1] * t[j][1]) + (t[j][2] * t[j][2] + t[j][3] * t[j][3]);
;         const float rs = rsqrtf(wave_sum(s) * (1.f / DM) + 1e-6f) * scale;
; #pragma unroll
;         for (int j = 0; j < 4; ++j) { const f32x4 g = *(const f32x4*)(gpost + 512 * (j >> 1) + 8 * lane + 4 * (j & 1)); R.v[j] = R.v[j] + t[j] * g * rs; } }
;     if (xo) {
; #pragma unroll
;         for (int j = 0; j < 4; ++j) __builtin_nontemporal_store(R.v[j], (f32x4*)(xo + 512 * (j >> 1) + 8 * lane + 4 * (j & 1))); }
;     if (hn) { float s = 0.f;
; #pragma unroll
;         for (int j = 0; j < 4; ++j) s += (R.v[j][0] * R.v[j][0] + R.v[j][1] * R.v[j][1]) + (R.v[j][2] * R.v[j][2] + R.v[j][3] * R.v[j][3]);
;         const float rs = rsqrtf(wave_sum(s) * (1.f / DM) + 1e-6f);
; #pragma unroll
;         for (int j = 0; j < 2; ++j) { const f32x4 g0 = *(const f32x4*)(gpre + 512 * j + 8 * lane), g1 = *(const f32x4*)(gpre + 512 * j + 8 * lane + 4); const f32x4 o0 = R.v[2 * j] * g0 * rs, o1 = R.v[2 * j + 1] * g1 * rs;
;             u32x4 w; w.x = cvt_pk_bf16(o0[0], o0[1]); w.y = cvt_pk_bf16(o0[2], o0[3]); w.z = cvt_pk_bf16(o1[0], o1[1]); w.w = cvt_pk_bf16(o1[2], o1[3]); *(u32x4*)(hn + 512 * j + 8 * lane) = w; } }
.Lrn_skip2:
	s_add_i32 s24, s24, s44
	s_cmp_gt_i32 s24, 0xffff
	s_cbranch_scc1 .Lrn_exit
	s_mul_i32 s25, s44, 3
	s_add_i32 s25, s25, s24
	s_cmp_lt_i32 s25, 0x10000
	s_cselect_b32 s25, s25, s24
	s_lshl_b32 s34, s25, 12
	s_lshl_b32 s4, s25, 11
	v_lshl_add_u64 v[228:229], v[62:63], 0, s[34:35]
	v_lshl_add_u64 v[230:231], v[52:53], 0, s[4:5]
	global_load_dwordx4 v[70:73], v[228:229], off nt
	global_load_dwordx4 v[74:77], v[228:229], off offset:1024 nt
	global_load_dwordx4 v[78:81], v[228:229], off offset:2048 nt
	global_load_dwordx4 v[82:85], v[228:229], off offset:3072 nt
	global_load_dwordx2 v[86:87], v[230:231], off nt
	global_load_dwordx2 v[88:89], v[230:231], off offset:512 nt
	global_load_dwordx2 v[90:91], v[230:231], off offset:1024 nt
	global_load_dwordx2 v[92:93], v[230:231], off offset:1536 nt
	s_lshl_b32 s18, s24, 12
	s_lshl_b32 s28, s24, 11
	s_andn2_b64 vcc, exec, s[40:41]
	s_waitcnt vmcnt(36)
	v_lshlrev_b32_e32 v206, 16, v178
	v_and_b32_e32 v207, 0xffff0000, v178
	v_lshlrev_b32_e32 v208, 16, v179
	v_and_b32_e32 v209, 0xffff0000, v179
	v_lshlrev_b32_e32 v210, 16, v180
	v_and_b32_e32 v211, 0xffff0000, v180
	v_lshlrev_b32_e32 v212, 16, v181
	v_and_b32_e32 v213, 0xffff0000, v181
	v_lshlrev_b32_e32 v214, 16, v182
	v_and_b32_e32 v215, 0xffff0000, v182
	v_lshlrev_b32_e32 v216, 16, v183
	v_and_b32_e32 v217, 0xffff0000, v183
	v_lshlrev_b32_e32 v218, 16, v184
	v_and_b32_e32 v219, 0xffff0000, v184
	v_lshlrev_b32_e32 v220, 16, v185
	v_and_b32_e32 v221, 0xffff0000, v185
	v_pk_mul_f32 v[222:223], v[206:207], v[206:207]
	v_pk_fma_f32 v[222:223], v[208:209], v[208:209], v[222:223]
	v_pk_fma_f32 v[222:223], v[210:211], v[210:211], v[222:223]
	v_pk_fma_f32 v[222:223], v[212:213], v[212:213], v[222:223]
	v_pk_fma_f32 v[222:223], v[214:215], v[214:215], v[222:223]
	v_pk_fma_f32 v[222:223], v[216:217], v[216:217], v[222:223]
	v_pk_fma_f32 v[222:223], v[218:219], v[218:219], v[222:223]
	v_pk_fma_f32 v[222:223], v[220:221], v[220:221], v[222:223]
	v_lshl_add_u64 v[228:229], v[56:57], 0, s[18:19]
	v_add_f32_e32 v224, v222, v223
	s_nop 1
	v_add_f32_dpp v224, v224, v224 quad_perm:[1,0,3,2] row_mask:0xf bank_mask:0xf bound_ctrl:1
	s_nop 1
	v_add_f32_dpp v224, v224, v224 quad_perm:[2,3,0,1] row_mask:0xf bank_mask:0xf bound_ctrl:1
	s_nop 1
	v_add_f32_dpp v224, v224, v224 row_half_mirror row_mask:0xf bank_mask:0xf bound_ctrl:1
	s_nop 1
	v_add_f32_dpp v224, v224, v224 row_mirror row_mask:0xf bank_mask:0xf bound_ctrl:1
	v_mov_b32_e32 v225, v224
	s_nop 1
	v_permlane16_swap_b32_e32 v224, v225
	v_add_f32_e32 v224, v224, v225
	v_mov_b32_e32 v225, v224
	s_nop 1
	v_permlane32_swap_b32_e32 v224, v225
	v_add_f32_e32 v224, v224, v225
	v_fmamk_f32 v224, v224, 0x3a800000, v197
	v_rsq_f32_e32 v224, v224
	v_lshl_add_u64 v[230:231], v[60:61], 0, s[28:29]
	v_mul_f32_e32 v226, v69, v224
	v_pk_mul_f32 v[206:207], v[206:207], v[96:97]
	v_pk_mul_f32 v[208:209], v[208:209], v[98:99]
	v_pk_mul_f32 v[210:211], v[210:211], v[100:101]
	v_pk_mul_f32 v[212:213], v[212:213], v[102:103]
	v_pk_mul_f32 v[214:215], v[214:215], v[104:105]
	v_pk_mul_f32 v[216:217], v[216:217], v[106:107]
	v_pk_mul_f32 v[218:219], v[218:219], v[108:109]
	v_pk_mul_f32 v[220:221], v[220:221], v[110:111]
	v_pk_fma_f32 v[162:163], v[206:207], v[226:227], v[162:163] op_sel_hi:[1,0,1]
	v_pk_fma_f32 v[164:165], v[208:209], v[226:227], v[164:165] op_sel_hi:[1,0,1]
	v_pk_fma_f32 v[166:167], v[210:211], v[226:227], v[166:167] op_sel_hi:[1,0,1]
	v_pk_fma_f32 v[168:169], v[212:213], v[226:227], v[168:169] op_sel_hi:[1,0,1]
	v_pk_fma_f32 v[170:171], v[214:215], v[226:227], v[170:171] op_sel_hi:[1,0,1]
	v_pk_fma_f32 v[172:173], v[216:217], v[226:227], v[172:173] op_sel_hi:[1,0,1]
	v_pk_fma_f32 v[174:175], v[218:219], v[226:227], v[174:175] op_sel_hi:[1,0,1]
	v_pk_fma_f32 v[176:177], v[220:221], v[226:227], v[176:177] op_sel_hi:[1,0,1]
	global_store_dwordx4 v[228:229], v[162:165], off nt
	global_store_dwordx4 v[228:229], v[166:169], off offset:1024 nt
	global_store_dwordx4 v[228:229], v[170:173], off offset:2048 nt
	global_store_dwordx4 v[228:229], v[174:177], off offset:3072 nt
	s_cbranch_vccnz .Lrn_skip3
	v_pk_mul_f32 v[222:223], v[162:163], v[162:163]
	v_pk_fma_f32 v[222:223], v[164:165], v[164:165], v[222:223]
	v_pk_fma_f32 v[222:223], v[166:167], v[166:167], v[222:223]
	v_pk_fma_f32 v[222:223], v[168:169], v[168:169], v[222:223]
	v_pk_fma_f32 v[222:223], v[170:171], v[170:171], v[222:223]
	v_pk_fma_f32 v[222:223], v[172:173], v[172:173], v[222:223]
	v_pk_fma_f32 v[222:223], v[174:175], v[174:175], v[222:223]
	v_pk_fma_f32 v[222:223], v[176:177], v[176:177], v[222:223]
	v_pk_mul_f32 v[232:233], v[162:163], v[112:113]
	v_pk_mul_f32 v[234:235], v[164:165], v[114:115]
	v_pk_mul_f32 v[236:237], v[166:167], v[116:117]
	v_pk_mul_f32 v[238:239], v[168:169], v[118:119]
	v_pk_mul_f32 v[240:241], v[170:171], v[120:121]
	v_pk_mul_f32 v[242:243], v[172:173], v[122:123]
	v_pk_mul_f32 v[244:245], v[174:175], v[124:125]
	v_pk_mul_f32 v[246:247], v[176:177], v[126:127]
	v_add_f32_e32 v224, v222, v223
	s_nop 1
	v_add_f32_dpp v224, v224, v224 quad_perm:[1,0,3,2] row_mask:0xf bank_mask:0xf bound_ctrl:1
	s_nop 1
	v_add_f32_dpp v224, v224, v224 quad_perm:[2,3,0,1] row_mask:0xf bank_mask:0xf bound_ctrl:1
	s_nop 1
	v_add_f32_dpp v224, v224, v224 row_half_mirror row_mask:0xf bank_mask:0xf bound_ctrl:1
	s_nop 1
	v_add_f32_dpp v224, v224, v224 row_mirror row_mask:0xf bank_mask:0xf bound_ctrl:1
	v_mov_b32_e32 v225, v224
	s_nop 1
	v_permlane16_swap_b32_e32 v224, v225
	v_add_f32_e32 v224, v224, v225
	v_mov_b32_e32 v225, v224
	s_nop 1
	v_permlane32_swap_b32_e32 v224, v225
	v_add_f32_e32 v224, v224, v225
	v_fmamk_f32 v224, v224, 0x3a800000, v197
	v_rsq_f32_e32 v226, v224
	s_nop 0
	v_pk_mul_f32 v[232:233], v[232:233], v[226:227] op_sel_hi:[1,0]
	v_pk_mul_f32 v[234:235], v[234:235], v[226:227] op_sel_hi:[1,0]
	v_pk_mul_f32 v[236:237], v[236:237], v[226:227] op_sel_hi:[1,0]
	v_pk_mul_f32 v[238:239], v[238:239], v[226:227] op_sel_hi:[1,0]
	v_pk_mul_f32 v[240:241], v[240:241], v[226:227] op_sel_hi:[1,0]
	v_pk_mul_f32 v[242:243], v[242:243], v[226:227] op_sel_hi:[1,0]
	v_pk_mul_f32 v[244:245], v[244:245], v[226:227] op_sel_hi:[1,0]
	v_pk_mul_f32 v[246:247], v[246:247], v[226:227] op_sel_hi:[1,0]
	v_cvt_pk_bf16_f32 v248, v232, v233
	v_cvt_pk_bf16_f32 v249, v234, v235
	global_store_dwordx2 v[230:231], v[248:249], off offset:0 sc1
	v_cvt_pk_bf16_f32 v250, v236, v237
	v_cvt_pk_bf16_f32 v251, v238, v239
	global_store_dwordx2 v[230:231], v[250:251], off offset:512 sc1
	v_cvt_pk_bf16_f32 v248, v240, v241
	v_cvt_pk_bf16_f32 v249, v242, v243
	global_store_dwordx2 v[230:231], v[248:249], off offset:1024 sc1
	v_cvt_pk_bf16_f32 v250, v244, v245
	v_cvt_pk_bf16_f32 v251, v246, v247
	global_store_dwordx2 v[230:231], v[250:251], off offset:1536 sc1
